# K-loops: the At LDS reads of the second super-phase interleaved pairwise with its six LDS-DMA issues (were 8 reads then 6 DMAs)
# speedup vs baseline: 1.0222x; 1.0102x over previous
.LBB0_318:
	v_add_u32_e32 v128, 0x10000, v251
	ds_read_b128 v[146:149], v128
	ds_read_b128 v[150:153], v128 offset:1024
	ds_read_b128 v[154:157], v128 offset:2048
	ds_read_b128 v[158:161], v128 offset:3072
	v_add_u32_e32 v128, 0x14000, v251
	ds_read_b128 v[130:133], v128
	ds_read_b128 v[134:137], v128 offset:1024
	ds_read_b128 v[138:141], v128 offset:2048
	ds_read_b128 v[142:145], v128 offset:3072
	s_cmp_eq_u32 s57, s3
	s_cselect_b32 s73, s55, s94
	s_cselect_b32 s72, s54, s93
	s_cselect_b32 s77, s63, s92
	s_cselect_b32 s76, s62, s8
	s_waitcnt lgkmcnt(0)
	ds_read_b128 v[162:165], v252
	ds_read_b128 v[166:169], v252 offset:1024
	ds_read_b128 v[170:173], v252 offset:2048
	ds_read_b128 v[174:177], v252 offset:3072
	ds_read_b128 v[178:181], v252 offset:4096
	ds_read_b128 v[182:185], v252 offset:5120
	ds_read_b128 v[186:189], v252 offset:6144
	ds_read_b128 v[190:193], v252 offset:7168
	s_add_u32 s42, s93, s9
	s_addc_u32 s43, s94, 0
	s_add_u32 s42, s42, 0xffffff80
	s_addc_u32 s43, s43, -1
	s_mov_b32 s74, m0
	s_mov_b32 m0, s65
	s_nop 0
	global_load_lds_dwordx4 v245, s[42:43]
	s_mov_b32 m0, s74
	s_nop 0
	s_mov_b32 s74, m0
	s_mov_b32 m0, s66
	s_nop 0
	global_load_lds_dwordx4 v247, s[42:43]
	s_mov_b32 m0, s74
	s_waitcnt vmcnt(8)
	s_waitcnt lgkmcnt(0)
	s_barrier
	s_setprio 1
	s_waitcnt lgkmcnt(0)
	v_mfma_f32_16x16x32_bf16 v[124:127], v[146:149], v[162:165], v[124:127]
	v_mfma_f32_16x16x32_bf16 v[120:123], v[154:157], v[162:165], v[120:123]
	v_mfma_f32_16x16x32_bf16 v[108:111], v[146:149], v[170:173], v[108:111]
	v_mfma_f32_16x16x32_bf16 v[104:107], v[154:157], v[170:173], v[104:107]
	v_mfma_f32_16x16x32_bf16 v[92:95], v[146:149], v[178:181], v[92:95]
	v_mfma_f32_16x16x32_bf16 v[88:91], v[154:157], v[178:181], v[88:91]
	v_mfma_f32_16x16x32_bf16 v[76:79], v[146:149], v[186:189], v[76:79]
	v_mfma_f32_16x16x32_bf16 v[72:75], v[154:157], v[186:189], v[72:75]
	v_mfma_f32_16x16x32_bf16 v[124:127], v[150:153], v[166:169], v[124:127]
	v_mfma_f32_16x16x32_bf16 v[120:123], v[158:161], v[166:169], v[120:123]
	v_mfma_f32_16x16x32_bf16 v[108:111], v[150:153], v[174:177], v[108:111]
	v_mfma_f32_16x16x32_bf16 v[104:107], v[158:161], v[174:177], v[104:107]
	v_mfma_f32_16x16x32_bf16 v[92:95], v[150:153], v[182:185], v[92:95]
	v_mfma_f32_16x16x32_bf16 v[88:91], v[158:161], v[182:185], v[88:91]
	v_mfma_f32_16x16x32_bf16 v[76:79], v[150:153], v[190:193], v[76:79]
	v_mfma_f32_16x16x32_bf16 v[72:75], v[158:161], v[190:193], v[72:75]
	s_setprio 0
	s_setprio 1
	v_mfma_f32_16x16x32_bf16 v[116:119], v[130:133], v[162:165], v[116:119]
	v_mfma_f32_16x16x32_bf16 v[112:115], v[138:141], v[162:165], v[112:115]
	v_mfma_f32_16x16x32_bf16 v[100:103], v[130:133], v[170:173], v[100:103]
	v_mfma_f32_16x16x32_bf16 v[96:99], v[138:141], v[170:173], v[96:99]
	v_mfma_f32_16x16x32_bf16 v[84:87], v[130:133], v[178:181], v[84:87]
	v_mfma_f32_16x16x32_bf16 v[80:83], v[138:141], v[178:181], v[80:83]
	v_mfma_f32_16x16x32_bf16 v[68:71], v[130:133], v[186:189], v[68:71]
	v_mfma_f32_16x16x32_bf16 v[64:67], v[138:141], v[186:189], v[64:67]
	v_mfma_f32_16x16x32_bf16 v[116:119], v[134:137], v[166:169], v[116:119]
	v_mfma_f32_16x16x32_bf16 v[112:115], v[142:145], v[166:169], v[112:115]
	v_mfma_f32_16x16x32_bf16 v[100:103], v[134:137], v[174:177], v[100:103]
	v_mfma_f32_16x16x32_bf16 v[96:99], v[142:145], v[174:177], v[96:99]
	v_mfma_f32_16x16x32_bf16 v[84:87], v[134:137], v[182:185], v[84:87]
	v_mfma_f32_16x16x32_bf16 v[80:83], v[142:145], v[182:185], v[80:83]
	v_mfma_f32_16x16x32_bf16 v[68:71], v[134:137], v[190:193], v[68:71]
	v_mfma_f32_16x16x32_bf16 v[64:67], v[142:145], v[190:193], v[64:67]
	s_setprio 0
	s_barrier
	s_mov_b32 s42, m0
	s_mov_b32 m0, s14
	s_nop 0
	global_load_lds_dwordx4 v246, s[76:77]
	s_mov_b32 m0, s42
	ds_read_b128 v[186:189], v252 offset:16384
	ds_read_b128 v[190:193], v252 offset:17408
	s_add_u32 s74, s76, s9
	s_mov_b32 s42, m0
	s_mov_b32 m0, s15
	s_nop 0
	global_load_lds_dwordx4 v248, s[76:77]
	s_mov_b32 m0, s42
	ds_read_b128 v[178:181], v252 offset:18432
	ds_read_b128 v[182:185], v252 offset:19456
	s_addc_u32 s75, s77, 0
	s_mov_b32 s42, m0
	s_mov_b32 m0, s16
	s_nop 0
	global_load_lds_dwordx4 v246, s[74:75]
	s_mov_b32 m0, s42
	ds_read_b128 v[170:173], v252 offset:20480
	ds_read_b128 v[174:177], v252 offset:21504
	v_cndmask_b32_e64 v128, 0, 1, s[68:69]
	s_mov_b32 s42, m0
	s_mov_b32 m0, s17
	s_nop 0
	global_load_lds_dwordx4 v248, s[74:75]
	s_mov_b32 m0, s42
	ds_read_b128 v[162:165], v252 offset:22528
	ds_read_b128 v[166:169], v252 offset:23552
	s_andn2_b64 vcc, exec, s[68:69]
	s_mov_b32 s42, m0
	s_mov_b32 m0, s11
	s_nop 0
	global_load_lds_dwordx4 v245, s[72:73]
	s_mov_b32 m0, s42
	s_nop 0
	s_mov_b32 s42, m0
	s_mov_b32 m0, s19
	s_nop 0
	global_load_lds_dwordx4 v247, s[72:73]
	s_mov_b32 m0, s42
	s_waitcnt vmcnt(8)
	s_waitcnt lgkmcnt(0)
	s_barrier
	v_cmp_ne_u32_e64 s[42:43], 1, v128
	s_cbranch_vccnz .LBB0_320
	s_setprio 1
	s_waitcnt lgkmcnt(0)
	v_mfma_f32_16x16x32_bf16 v[60:63], v[146:149], v[186:189], v[60:63]
	v_mfma_f32_16x16x32_bf16 v[56:59], v[154:157], v[186:189], v[56:59]
	v_mfma_f32_16x16x32_bf16 v[44:47], v[146:149], v[178:181], v[44:47]
	v_mfma_f32_16x16x32_bf16 v[40:43], v[154:157], v[178:181], v[40:43]
	v_mfma_f32_16x16x32_bf16 v[28:31], v[146:149], v[170:173], v[28:31]
	v_mfma_f32_16x16x32_bf16 v[24:27], v[154:157], v[170:173], v[24:27]
	v_mfma_f32_16x16x32_bf16 v[12:15], v[146:149], v[162:165], v[12:15]
	v_mfma_f32_16x16x32_bf16 v[8:11], v[154:157], v[162:165], v[8:11]
	v_mfma_f32_16x16x32_bf16 v[60:63], v[150:153], v[190:193], v[60:63]
	v_mfma_f32_16x16x32_bf16 v[56:59], v[158:161], v[190:193], v[56:59]
	v_mfma_f32_16x16x32_bf16 v[44:47], v[150:153], v[182:185], v[44:47]
	v_mfma_f32_16x16x32_bf16 v[40:43], v[158:161], v[182:185], v[40:43]
	v_mfma_f32_16x16x32_bf16 v[28:31], v[150:153], v[174:177], v[28:31]
	v_mfma_f32_16x16x32_bf16 v[24:27], v[158:161], v[174:177], v[24:27]
	v_mfma_f32_16x16x32_bf16 v[12:15], v[150:153], v[166:169], v[12:15]
	v_mfma_f32_16x16x32_bf16 v[8:11], v[158:161], v[166:169], v[8:11]
	s_setprio 0
	s_setprio 1
	v_mfma_f32_16x16x32_bf16 v[52:55], v[130:133], v[186:189], v[52:55]
	v_mfma_f32_16x16x32_bf16 v[48:51], v[138:141], v[186:189], v[48:51]
	v_mfma_f32_16x16x32_bf16 v[36:39], v[130:133], v[178:181], v[36:39]
	v_mfma_f32_16x16x32_bf16 v[32:35], v[138:141], v[178:181], v[32:35]
	v_mfma_f32_16x16x32_bf16 v[20:23], v[130:133], v[170:173], v[20:23]
	v_mfma_f32_16x16x32_bf16 v[16:19], v[138:141], v[170:173], v[16:19]
	v_mfma_f32_16x16x32_bf16 v[4:7], v[130:133], v[162:165], v[4:7]
	v_mfma_f32_16x16x32_bf16 v[0:3], v[138:141], v[162:165], v[0:3]
	v_mfma_f32_16x16x32_bf16 v[52:55], v[134:137], v[190:193], v[52:55]
	v_mfma_f32_16x16x32_bf16 v[48:51], v[142:145], v[190:193], v[48:51]
	v_mfma_f32_16x16x32_bf16 v[36:39], v[134:137], v[182:185], v[36:39]
	v_mfma_f32_16x16x32_bf16 v[32:35], v[142:145], v[182:185], v[32:35]
	v_mfma_f32_16x16x32_bf16 v[20:23], v[134:137], v[174:177], v[20:23]
	v_mfma_f32_16x16x32_bf16 v[16:19], v[142:145], v[174:177], v[16:19]
	v_mfma_f32_16x16x32_bf16 v[4:7], v[134:137], v[166:169], v[4:7]
	v_mfma_f32_16x16x32_bf16 v[0:3], v[142:145], v[166:169], v[0:3]
	s_setprio 0
.LBB0_320:
	s_add_u32 s80, s72, 0x80
	s_addc_u32 s81, s73, 0
	s_add_u32 s76, s76, 0x80
	s_addc_u32 s77, s77, 0
	s_barrier
	v_add_u32_e32 v128, 0x18000, v251
	ds_read_b128 v[146:149], v128
	ds_read_b128 v[150:153], v128 offset:1024
	ds_read_b128 v[154:157], v128 offset:2048
	ds_read_b128 v[158:161], v128 offset:3072
	v_add_u32_e32 v128, 0x1c000, v251
	ds_read_b128 v[130:133], v128
	ds_read_b128 v[134:137], v128 offset:1024
	ds_read_b128 v[138:141], v128 offset:2048
	ds_read_b128 v[142:145], v128 offset:3072
	s_waitcnt lgkmcnt(0)
	ds_read_b128 v[162:165], v252 offset:32768
	ds_read_b128 v[166:169], v252 offset:33792
	ds_read_b128 v[170:173], v252 offset:34816
	ds_read_b128 v[174:177], v252 offset:35840
	ds_read_b128 v[178:181], v252 offset:36864
	ds_read_b128 v[182:185], v252 offset:37888
	ds_read_b128 v[186:189], v252 offset:38912
	ds_read_b128 v[190:193], v252 offset:39936
	s_add_u32 s72, s72, s9
	s_addc_u32 s73, s73, 0
	s_mov_b32 s95, m0
	s_mov_b32 m0, s20
	s_nop 0
	global_load_lds_dwordx4 v245, s[72:73]
	s_mov_b32 m0, s95
	s_nop 0
	s_mov_b32 s95, m0
	s_mov_b32 m0, s21
	s_nop 0
	global_load_lds_dwordx4 v247, s[72:73]
	s_mov_b32 m0, s95
	s_waitcnt vmcnt(8)
	s_waitcnt lgkmcnt(0)
	s_barrier
	s_setprio 1
	s_waitcnt lgkmcnt(0)
	v_mfma_f32_16x16x32_bf16 v[124:127], v[146:149], v[162:165], v[124:127]
	v_mfma_f32_16x16x32_bf16 v[120:123], v[154:157], v[162:165], v[120:123]
	v_mfma_f32_16x16x32_bf16 v[108:111], v[146:149], v[170:173], v[108:111]
	v_mfma_f32_16x16x32_bf16 v[104:107], v[154:157], v[170:173], v[104:107]
	v_mfma_f32_16x16x32_bf16 v[92:95], v[146:149], v[178:181], v[92:95]
	v_mfma_f32_16x16x32_bf16 v[88:91], v[154:157], v[178:181], v[88:91]
	v_mfma_f32_16x16x32_bf16 v[76:79], v[146:149], v[186:189], v[76:79]
	v_mfma_f32_16x16x32_bf16 v[72:75], v[154:157], v[186:189], v[72:75]
	v_mfma_f32_16x16x32_bf16 v[124:127], v[150:153], v[166:169], v[124:127]
	v_mfma_f32_16x16x32_bf16 v[120:123], v[158:161], v[166:169], v[120:123]
	v_mfma_f32_16x16x32_bf16 v[108:111], v[150:153], v[174:177], v[108:111]
	v_mfma_f32_16x16x32_bf16 v[104:107], v[158:161], v[174:177], v[104:107]
	v_mfma_f32_16x16x32_bf16 v[92:95], v[150:153], v[182:185], v[92:95]
	v_mfma_f32_16x16x32_bf16 v[88:91], v[158:161], v[182:185], v[88:91]
	v_mfma_f32_16x16x32_bf16 v[76:79], v[150:153], v[190:193], v[76:79]
	v_mfma_f32_16x16x32_bf16 v[72:75], v[158:161], v[190:193], v[72:75]
	s_setprio 0
	s_setprio 1
	v_mfma_f32_16x16x32_bf16 v[116:119], v[130:133], v[162:165], v[116:119]
	v_mfma_f32_16x16x32_bf16 v[112:115], v[138:141], v[162:165], v[112:115]
	v_mfma_f32_16x16x32_bf16 v[100:103], v[130:133], v[170:173], v[100:103]
	v_mfma_f32_16x16x32_bf16 v[96:99], v[138:141], v[170:173], v[96:99]
	v_mfma_f32_16x16x32_bf16 v[84:87], v[130:133], v[178:181], v[84:87]
	v_mfma_f32_16x16x32_bf16 v[80:83], v[138:141], v[178:181], v[80:83]
	v_mfma_f32_16x16x32_bf16 v[68:71], v[130:133], v[186:189], v[68:71]
	v_mfma_f32_16x16x32_bf16 v[64:67], v[138:141], v[186:189], v[64:67]
	v_mfma_f32_16x16x32_bf16 v[116:119], v[134:137], v[166:169], v[116:119]
	v_mfma_f32_16x16x32_bf16 v[112:115], v[142:145], v[166:169], v[112:115]
	v_mfma_f32_16x16x32_bf16 v[100:103], v[134:137], v[174:177], v[100:103]
	v_mfma_f32_16x16x32_bf16 v[96:99], v[142:145], v[174:177], v[96:99]
	v_mfma_f32_16x16x32_bf16 v[84:87], v[134:137], v[182:185], v[84:87]
	v_mfma_f32_16x16x32_bf16 v[80:83], v[142:145], v[182:185], v[80:83]
	v_mfma_f32_16x16x32_bf16 v[68:71], v[134:137], v[190:193], v[68:71]
	v_mfma_f32_16x16x32_bf16 v[64:67], v[142:145], v[190:193], v[64:67]
	s_setprio 0
	s_barrier
	s_mov_b32 s72, m0
	s_mov_b32 m0, s23
	s_nop 0
	global_load_lds_dwordx4 v246, s[76:77]
	s_mov_b32 m0, s72
	ds_read_b128 v[186:189], v252 offset:49152
	ds_read_b128 v[190:193], v252 offset:50176
	s_nop 0
	s_mov_b32 s72, m0
	s_mov_b32 m0, s30
	s_nop 0
	global_load_lds_dwordx4 v248, s[76:77]
	s_mov_b32 m0, s72
	ds_read_b128 v[178:181], v252 offset:51200
	ds_read_b128 v[182:185], v252 offset:52224
	s_add_u32 s72, s74, 0x80
	s_addc_u32 s73, s75, 0
	s_mov_b32 s74, m0
	s_mov_b32 m0, s52
	s_nop 0
	global_load_lds_dwordx4 v246, s[72:73]
	s_mov_b32 m0, s74
	ds_read_b128 v[170:173], v252 offset:53248
	ds_read_b128 v[174:177], v252 offset:54272
	s_and_b64 vcc, exec, s[42:43]
	s_mov_b32 s74, m0
	s_mov_b32 m0, s53
	s_nop 0
	global_load_lds_dwordx4 v248, s[72:73]
	s_mov_b32 m0, s74
	ds_read_b128 v[162:165], v252 offset:55296
	ds_read_b128 v[166:169], v252 offset:56320
	s_mov_b32 s72, m0
	s_mov_b32 m0, s47
	s_nop 0
	global_load_lds_dwordx4 v245, s[80:81]
	s_mov_b32 m0, s72
	s_nop 0
	s_mov_b32 s72, m0
	s_mov_b32 m0, s50
	s_nop 0
	global_load_lds_dwordx4 v247, s[80:81]
	s_mov_b32 m0, s72
	s_waitcnt vmcnt(8)
	s_waitcnt lgkmcnt(0)
	s_barrier
	s_cbranch_vccnz .LBB0_317
	s_setprio 1
	s_waitcnt lgkmcnt(0)
	v_mfma_f32_16x16x32_bf16 v[60:63], v[146:149], v[186:189], v[60:63]
	v_mfma_f32_16x16x32_bf16 v[56:59], v[154:157], v[186:189], v[56:59]
	v_mfma_f32_16x16x32_bf16 v[44:47], v[146:149], v[178:181], v[44:47]
	v_mfma_f32_16x16x32_bf16 v[40:43], v[154:157], v[178:181], v[40:43]
	v_mfma_f32_16x16x32_bf16 v[28:31], v[146:149], v[170:173], v[28:31]
	v_mfma_f32_16x16x32_bf16 v[24:27], v[154:157], v[170:173], v[24:27]
	v_mfma_f32_16x16x32_bf16 v[12:15], v[146:149], v[162:165], v[12:15]
	v_mfma_f32_16x16x32_bf16 v[8:11], v[154:157], v[162:165], v[8:11]
	v_mfma_f32_16x16x32_bf16 v[60:63], v[150:153], v[190:193], v[60:63]
	v_mfma_f32_16x16x32_bf16 v[56:59], v[158:161], v[190:193], v[56:59]
	v_mfma_f32_16x16x32_bf16 v[44:47], v[150:153], v[182:185], v[44:47]
	v_mfma_f32_16x16x32_bf16 v[40:43], v[158:161], v[182:185], v[40:43]
	v_mfma_f32_16x16x32_bf16 v[28:31], v[150:153], v[174:177], v[28:31]
	v_mfma_f32_16x16x32_bf16 v[24:27], v[158:161], v[174:177], v[24:27]
	v_mfma_f32_16x16x32_bf16 v[12:15], v[150:153], v[166:169], v[12:15]
	v_mfma_f32_16x16x32_bf16 v[8:11], v[158:161], v[166:169], v[8:11]
	s_setprio 0
	s_setprio 1
	v_mfma_f32_16x16x32_bf16 v[52:55], v[130:133], v[186:189], v[52:55]
	v_mfma_f32_16x16x32_bf16 v[48:51], v[138:141], v[186:189], v[48:51]
	v_mfma_f32_16x16x32_bf16 v[36:39], v[130:133], v[178:181], v[36:39]
	v_mfma_f32_16x16x32_bf16 v[32:35], v[138:141], v[178:181], v[32:35]
	v_mfma_f32_16x16x32_bf16 v[20:23], v[130:133], v[170:173], v[20:23]
	v_mfma_f32_16x16x32_bf16 v[16:19], v[138:141], v[170:173], v[16:19]
	v_mfma_f32_16x16x32_bf16 v[4:7], v[130:133], v[162:165], v[4:7]
	v_mfma_f32_16x16x32_bf16 v[0:3], v[138:141], v[162:165], v[0:3]
	v_mfma_f32_16x16x32_bf16 v[52:55], v[134:137], v[190:193], v[52:55]
	v_mfma_f32_16x16x32_bf16 v[48:51], v[142:145], v[190:193], v[48:51]
	v_mfma_f32_16x16x32_bf16 v[36:39], v[134:137], v[182:185], v[36:39]
	v_mfma_f32_16x16x32_bf16 v[32:35], v[142:145], v[182:185], v[32:35]
	v_mfma_f32_16x16x32_bf16 v[20:23], v[134:137], v[174:177], v[20:23]
	v_mfma_f32_16x16x32_bf16 v[16:19], v[142:145], v[174:177], v[16:19]
	v_mfma_f32_16x16x32_bf16 v[4:7], v[134:137], v[166:169], v[4:7]
	v_mfma_f32_16x16x32_bf16 v[0:3], v[142:145], v[166:169], v[0:3]
	s_setprio 0
	s_branch .LBB0_317

.LBB0_413:
	v_add_u32_e32 v128, 0x10000, v208
	ds_read_b128 v[146:149], v128
	ds_read_b128 v[150:153], v128 offset:1024
	ds_read_b128 v[154:157], v128 offset:2048
	ds_read_b128 v[158:161], v128 offset:3072
	v_add_u32_e32 v128, 0x14000, v208
	ds_read_b128 v[130:133], v128
	ds_read_b128 v[134:137], v128 offset:1024
	ds_read_b128 v[138:141], v128 offset:2048
	ds_read_b128 v[142:145], v128 offset:3072
	s_add_u32 s38, s46, 0xfffc0080
	s_addc_u32 s39, s47, -1
	s_cmp_eq_u32 s19, 12
	s_cselect_b32 s75, s27, s39
	s_cselect_b32 s74, s99, s38
	s_cselect_b32 s63, s23, s18
	s_cselect_b32 s62, s3, s8
	s_waitcnt lgkmcnt(0)
	ds_read_b128 v[162:165], v209
	ds_read_b128 v[166:169], v209 offset:1024
	ds_read_b128 v[170:173], v209 offset:2048
	ds_read_b128 v[174:177], v209 offset:3072
	ds_read_b128 v[178:181], v209 offset:4096
	ds_read_b128 v[182:185], v209 offset:5120
	ds_read_b128 v[186:189], v209 offset:6144
	ds_read_b128 v[190:193], v209 offset:7168
	s_mov_b32 s38, m0
	s_mov_b32 m0, s30
	s_nop 0
	global_load_lds_dwordx4 v195, s[46:47]
	s_mov_b32 m0, s38
	s_nop 0
	s_mov_b32 s38, m0
	s_mov_b32 m0, s14
	s_nop 0
	global_load_lds_dwordx4 v197, s[46:47]
	s_mov_b32 m0, s38
	s_waitcnt vmcnt(8)
	s_waitcnt lgkmcnt(0)
	s_barrier
	s_setprio 1
	s_waitcnt lgkmcnt(0)
	v_mfma_f32_16x16x32_bf16 v[124:127], v[146:149], v[162:165], v[124:127]
	v_mfma_f32_16x16x32_bf16 v[120:123], v[154:157], v[162:165], v[120:123]
	v_mfma_f32_16x16x32_bf16 v[108:111], v[146:149], v[170:173], v[108:111]
	v_mfma_f32_16x16x32_bf16 v[104:107], v[154:157], v[170:173], v[104:107]
	v_mfma_f32_16x16x32_bf16 v[92:95], v[146:149], v[178:181], v[92:95]
	v_mfma_f32_16x16x32_bf16 v[88:91], v[154:157], v[178:181], v[88:91]
	v_mfma_f32_16x16x32_bf16 v[76:79], v[146:149], v[186:189], v[76:79]
	v_mfma_f32_16x16x32_bf16 v[72:75], v[154:157], v[186:189], v[72:75]
	v_mfma_f32_16x16x32_bf16 v[124:127], v[150:153], v[166:169], v[124:127]
	v_mfma_f32_16x16x32_bf16 v[120:123], v[158:161], v[166:169], v[120:123]
	v_mfma_f32_16x16x32_bf16 v[108:111], v[150:153], v[174:177], v[108:111]
	v_mfma_f32_16x16x32_bf16 v[104:107], v[158:161], v[174:177], v[104:107]
	v_mfma_f32_16x16x32_bf16 v[92:95], v[150:153], v[182:185], v[92:95]
	v_mfma_f32_16x16x32_bf16 v[88:91], v[158:161], v[182:185], v[88:91]
	v_mfma_f32_16x16x32_bf16 v[76:79], v[150:153], v[190:193], v[76:79]
	v_mfma_f32_16x16x32_bf16 v[72:75], v[158:161], v[190:193], v[72:75]
	s_setprio 0
	s_setprio 1
	v_mfma_f32_16x16x32_bf16 v[116:119], v[130:133], v[162:165], v[116:119]
	v_mfma_f32_16x16x32_bf16 v[112:115], v[138:141], v[162:165], v[112:115]
	v_mfma_f32_16x16x32_bf16 v[100:103], v[130:133], v[170:173], v[100:103]
	v_mfma_f32_16x16x32_bf16 v[96:99], v[138:141], v[170:173], v[96:99]
	v_mfma_f32_16x16x32_bf16 v[84:87], v[130:133], v[178:181], v[84:87]
	v_mfma_f32_16x16x32_bf16 v[80:83], v[138:141], v[178:181], v[80:83]
	v_mfma_f32_16x16x32_bf16 v[68:71], v[130:133], v[186:189], v[68:71]
	v_mfma_f32_16x16x32_bf16 v[64:67], v[138:141], v[186:189], v[64:67]
	v_mfma_f32_16x16x32_bf16 v[116:119], v[134:137], v[166:169], v[116:119]
	v_mfma_f32_16x16x32_bf16 v[112:115], v[142:145], v[166:169], v[112:115]
	v_mfma_f32_16x16x32_bf16 v[100:103], v[134:137], v[174:177], v[100:103]
	v_mfma_f32_16x16x32_bf16 v[96:99], v[142:145], v[174:177], v[96:99]
	v_mfma_f32_16x16x32_bf16 v[84:87], v[134:137], v[182:185], v[84:87]
	v_mfma_f32_16x16x32_bf16 v[80:83], v[142:145], v[182:185], v[80:83]
	v_mfma_f32_16x16x32_bf16 v[68:71], v[134:137], v[190:193], v[68:71]
	v_mfma_f32_16x16x32_bf16 v[64:67], v[142:145], v[190:193], v[64:67]
	s_setprio 0
	s_barrier
	s_mov_b32 s38, m0
	s_mov_b32 m0, s67
	s_nop 0
	global_load_lds_dwordx4 v196, s[62:63]
	s_mov_b32 m0, s38
	ds_read_b128 v[186:189], v209 offset:16384
	ds_read_b128 v[190:193], v209 offset:17408
	s_add_u32 s44, s62, 0x40000
	s_mov_b32 s38, m0
	s_mov_b32 m0, s86
	s_nop 0
	global_load_lds_dwordx4 v198, s[62:63]
	s_mov_b32 m0, s38
	ds_read_b128 v[178:181], v209 offset:18432
	ds_read_b128 v[182:185], v209 offset:19456
	s_addc_u32 s45, s63, 0
	s_mov_b32 s38, m0
	s_mov_b32 m0, s87
	s_nop 0
	global_load_lds_dwordx4 v196, s[44:45]
	s_mov_b32 m0, s38
	ds_read_b128 v[170:173], v209 offset:20480
	ds_read_b128 v[174:177], v209 offset:21504
	v_cndmask_b32_e64 v128, 0, 1, s[72:73]
	s_mov_b32 s38, m0
	s_mov_b32 m0, s88
	s_nop 0
	global_load_lds_dwordx4 v198, s[44:45]
	s_mov_b32 m0, s38
	ds_read_b128 v[162:165], v209 offset:22528
	ds_read_b128 v[166:169], v209 offset:23552
	v_cmp_ne_u32_e64 s[44:45], 1, v128
	s_mov_b32 s38, m0
	s_mov_b32 m0, s51
	s_nop 0
	global_load_lds_dwordx4 v195, s[74:75]
	s_mov_b32 m0, s38
	s_andn2_b64 vcc, exec, s[72:73]
	s_mov_b32 s38, m0
	s_mov_b32 m0, s89
	s_nop 0
	global_load_lds_dwordx4 v197, s[74:75]
	s_mov_b32 m0, s38
	s_waitcnt vmcnt(8)
	s_waitcnt lgkmcnt(0)
	s_barrier
	s_cbranch_vccnz .LBB0_415
	s_setprio 1
	s_waitcnt lgkmcnt(0)
	v_mfma_f32_16x16x32_bf16 v[60:63], v[146:149], v[186:189], v[60:63]
	v_mfma_f32_16x16x32_bf16 v[56:59], v[154:157], v[186:189], v[56:59]
	v_mfma_f32_16x16x32_bf16 v[44:47], v[146:149], v[178:181], v[44:47]
	v_mfma_f32_16x16x32_bf16 v[40:43], v[154:157], v[178:181], v[40:43]
	v_mfma_f32_16x16x32_bf16 v[28:31], v[146:149], v[170:173], v[28:31]
	v_mfma_f32_16x16x32_bf16 v[24:27], v[154:157], v[170:173], v[24:27]
	v_mfma_f32_16x16x32_bf16 v[12:15], v[146:149], v[162:165], v[12:15]
	v_mfma_f32_16x16x32_bf16 v[8:11], v[154:157], v[162:165], v[8:11]
	v_mfma_f32_16x16x32_bf16 v[60:63], v[150:153], v[190:193], v[60:63]
	v_mfma_f32_16x16x32_bf16 v[56:59], v[158:161], v[190:193], v[56:59]
	v_mfma_f32_16x16x32_bf16 v[44:47], v[150:153], v[182:185], v[44:47]
	v_mfma_f32_16x16x32_bf16 v[40:43], v[158:161], v[182:185], v[40:43]
	v_mfma_f32_16x16x32_bf16 v[28:31], v[150:153], v[174:177], v[28:31]
	v_mfma_f32_16x16x32_bf16 v[24:27], v[158:161], v[174:177], v[24:27]
	v_mfma_f32_16x16x32_bf16 v[12:15], v[150:153], v[166:169], v[12:15]
	v_mfma_f32_16x16x32_bf16 v[8:11], v[158:161], v[166:169], v[8:11]
	s_setprio 0
	s_setprio 1
	v_mfma_f32_16x16x32_bf16 v[52:55], v[130:133], v[186:189], v[52:55]
	v_mfma_f32_16x16x32_bf16 v[48:51], v[138:141], v[186:189], v[48:51]
	v_mfma_f32_16x16x32_bf16 v[36:39], v[130:133], v[178:181], v[36:39]
	v_mfma_f32_16x16x32_bf16 v[32:35], v[138:141], v[178:181], v[32:35]
	v_mfma_f32_16x16x32_bf16 v[20:23], v[130:133], v[170:173], v[20:23]
	v_mfma_f32_16x16x32_bf16 v[16:19], v[138:141], v[170:173], v[16:19]
	v_mfma_f32_16x16x32_bf16 v[4:7], v[130:133], v[162:165], v[4:7]
	v_mfma_f32_16x16x32_bf16 v[0:3], v[138:141], v[162:165], v[0:3]
	v_mfma_f32_16x16x32_bf16 v[52:55], v[134:137], v[190:193], v[52:55]
	v_mfma_f32_16x16x32_bf16 v[48:51], v[142:145], v[190:193], v[48:51]
	v_mfma_f32_16x16x32_bf16 v[36:39], v[134:137], v[182:185], v[36:39]
	v_mfma_f32_16x16x32_bf16 v[32:35], v[142:145], v[182:185], v[32:35]
	v_mfma_f32_16x16x32_bf16 v[20:23], v[134:137], v[174:177], v[20:23]
	v_mfma_f32_16x16x32_bf16 v[16:19], v[142:145], v[174:177], v[16:19]
	v_mfma_f32_16x16x32_bf16 v[4:7], v[134:137], v[166:169], v[4:7]
	v_mfma_f32_16x16x32_bf16 v[0:3], v[142:145], v[166:169], v[0:3]
	s_setprio 0
.LBB0_415:
	s_add_u32 s76, s74, 0x80
	s_addc_u32 s77, s75, 0
	s_add_u32 s38, s62, 0x80
	s_addc_u32 s39, s63, 0
	s_barrier
	v_add_u32_e32 v128, 0x18000, v208
	ds_read_b128 v[146:149], v128
	ds_read_b128 v[150:153], v128 offset:1024
	ds_read_b128 v[154:157], v128 offset:2048
	ds_read_b128 v[158:161], v128 offset:3072
	v_add_u32_e32 v128, 0x1c000, v208
	ds_read_b128 v[130:133], v128
	ds_read_b128 v[134:137], v128 offset:1024
	ds_read_b128 v[138:141], v128 offset:2048
	ds_read_b128 v[142:145], v128 offset:3072
	s_waitcnt lgkmcnt(0)
	ds_read_b128 v[162:165], v209 offset:32768
	ds_read_b128 v[166:169], v209 offset:33792
	ds_read_b128 v[170:173], v209 offset:34816
	ds_read_b128 v[174:177], v209 offset:35840
	ds_read_b128 v[178:181], v209 offset:36864
	ds_read_b128 v[182:185], v209 offset:37888
	ds_read_b128 v[186:189], v209 offset:38912
	ds_read_b128 v[190:193], v209 offset:39936
	s_add_u32 s74, s74, 0x40000
	s_addc_u32 s75, s75, 0
	s_mov_b32 vcc_lo, m0
	s_mov_b32 m0, s92
	s_nop 0
	global_load_lds_dwordx4 v195, s[74:75]
	s_mov_b32 m0, vcc_lo
	s_nop 0
	s_mov_b32 vcc_lo, m0
	s_mov_b32 m0, s93
	s_nop 0
	global_load_lds_dwordx4 v197, s[74:75]
	s_mov_b32 m0, vcc_lo
	s_waitcnt vmcnt(8)
	s_waitcnt lgkmcnt(0)
	s_barrier
	s_setprio 1
	s_waitcnt lgkmcnt(0)
	v_mfma_f32_16x16x32_bf16 v[124:127], v[146:149], v[162:165], v[124:127]
	v_mfma_f32_16x16x32_bf16 v[120:123], v[154:157], v[162:165], v[120:123]
	v_mfma_f32_16x16x32_bf16 v[108:111], v[146:149], v[170:173], v[108:111]
	v_mfma_f32_16x16x32_bf16 v[104:107], v[154:157], v[170:173], v[104:107]
	v_mfma_f32_16x16x32_bf16 v[92:95], v[146:149], v[178:181], v[92:95]
	v_mfma_f32_16x16x32_bf16 v[88:91], v[154:157], v[178:181], v[88:91]
	v_mfma_f32_16x16x32_bf16 v[76:79], v[146:149], v[186:189], v[76:79]
	v_mfma_f32_16x16x32_bf16 v[72:75], v[154:157], v[186:189], v[72:75]
	v_mfma_f32_16x16x32_bf16 v[124:127], v[150:153], v[166:169], v[124:127]
	v_mfma_f32_16x16x32_bf16 v[120:123], v[158:161], v[166:169], v[120:123]
	v_mfma_f32_16x16x32_bf16 v[108:111], v[150:153], v[174:177], v[108:111]
	v_mfma_f32_16x16x32_bf16 v[104:107], v[158:161], v[174:177], v[104:107]
	v_mfma_f32_16x16x32_bf16 v[92:95], v[150:153], v[182:185], v[92:95]
	v_mfma_f32_16x16x32_bf16 v[88:91], v[158:161], v[182:185], v[88:91]
	v_mfma_f32_16x16x32_bf16 v[76:79], v[150:153], v[190:193], v[76:79]
	v_mfma_f32_16x16x32_bf16 v[72:75], v[158:161], v[190:193], v[72:75]
	s_setprio 0
	s_setprio 1
	v_mfma_f32_16x16x32_bf16 v[116:119], v[130:133], v[162:165], v[116:119]
	v_mfma_f32_16x16x32_bf16 v[112:115], v[138:141], v[162:165], v[112:115]
	v_mfma_f32_16x16x32_bf16 v[100:103], v[130:133], v[170:173], v[100:103]
	v_mfma_f32_16x16x32_bf16 v[96:99], v[138:141], v[170:173], v[96:99]
	v_mfma_f32_16x16x32_bf16 v[84:87], v[130:133], v[178:181], v[84:87]
	v_mfma_f32_16x16x32_bf16 v[80:83], v[138:141], v[178:181], v[80:83]
	v_mfma_f32_16x16x32_bf16 v[68:71], v[130:133], v[186:189], v[68:71]
	v_mfma_f32_16x16x32_bf16 v[64:67], v[138:141], v[186:189], v[64:67]
	v_mfma_f32_16x16x32_bf16 v[116:119], v[134:137], v[166:169], v[116:119]
	v_mfma_f32_16x16x32_bf16 v[112:115], v[142:145], v[166:169], v[112:115]
	v_mfma_f32_16x16x32_bf16 v[100:103], v[134:137], v[174:177], v[100:103]
	v_mfma_f32_16x16x32_bf16 v[96:99], v[142:145], v[174:177], v[96:99]
	v_mfma_f32_16x16x32_bf16 v[84:87], v[134:137], v[182:185], v[84:87]
	v_mfma_f32_16x16x32_bf16 v[80:83], v[142:145], v[182:185], v[80:83]
	v_mfma_f32_16x16x32_bf16 v[68:71], v[134:137], v[190:193], v[68:71]
	v_mfma_f32_16x16x32_bf16 v[64:67], v[142:145], v[190:193], v[64:67]
	s_setprio 0
	s_barrier
	s_mov_b32 s74, m0
	s_mov_b32 m0, s95
	s_nop 0
	global_load_lds_dwordx4 v196, s[38:39]
	s_mov_b32 m0, s74
	ds_read_b128 v[186:189], v209 offset:49152
	ds_read_b128 v[190:193], v209 offset:50176
	s_nop 0
	s_mov_b32 s74, m0
	s_mov_b32 m0, s96
	s_nop 0
	global_load_lds_dwordx4 v198, s[38:39]
	s_mov_b32 m0, s74
	ds_read_b128 v[178:181], v209 offset:51200
	ds_read_b128 v[182:185], v209 offset:52224
	s_add_u32 s38, s62, 0x40080
	s_addc_u32 s39, s63, 0
	s_mov_b32 s62, m0
	s_mov_b32 m0, s65
	s_nop 0
	global_load_lds_dwordx4 v196, s[38:39]
	s_mov_b32 m0, s62
	ds_read_b128 v[170:173], v209 offset:53248
	ds_read_b128 v[174:177], v209 offset:54272
	s_and_b64 vcc, exec, s[44:45]
	s_mov_b32 s62, m0
	s_mov_b32 m0, s50
	s_nop 0
	global_load_lds_dwordx4 v198, s[38:39]
	s_mov_b32 m0, s62
	ds_read_b128 v[162:165], v209 offset:55296
	ds_read_b128 v[166:169], v209 offset:56320
	s_mov_b32 s38, m0
	s_mov_b32 m0, s97
	s_nop 0
	global_load_lds_dwordx4 v195, s[76:77]
	s_mov_b32 m0, s38
	s_nop 0
	s_mov_b32 s38, m0
	s_mov_b32 m0, s9
	s_nop 0
	global_load_lds_dwordx4 v197, s[76:77]
	s_mov_b32 m0, s38
	s_waitcnt vmcnt(8)
	s_waitcnt lgkmcnt(0)
	s_barrier
	s_cbranch_vccnz .LBB0_412
	s_setprio 1
	s_waitcnt lgkmcnt(0)
	v_mfma_f32_16x16x32_bf16 v[60:63], v[146:149], v[186:189], v[60:63]
	v_mfma_f32_16x16x32_bf16 v[56:59], v[154:157], v[186:189], v[56:59]
	v_mfma_f32_16x16x32_bf16 v[44:47], v[146:149], v[178:181], v[44:47]
	v_mfma_f32_16x16x32_bf16 v[40:43], v[154:157], v[178:181], v[40:43]
	v_mfma_f32_16x16x32_bf16 v[28:31], v[146:149], v[170:173], v[28:31]
	v_mfma_f32_16x16x32_bf16 v[24:27], v[154:157], v[170:173], v[24:27]
	v_mfma_f32_16x16x32_bf16 v[12:15], v[146:149], v[162:165], v[12:15]
	v_mfma_f32_16x16x32_bf16 v[8:11], v[154:157], v[162:165], v[8:11]
	v_mfma_f32_16x16x32_bf16 v[60:63], v[150:153], v[190:193], v[60:63]
	v_mfma_f32_16x16x32_bf16 v[56:59], v[158:161], v[190:193], v[56:59]
	v_mfma_f32_16x16x32_bf16 v[44:47], v[150:153], v[182:185], v[44:47]
	v_mfma_f32_16x16x32_bf16 v[40:43], v[158:161], v[182:185], v[40:43]
	v_mfma_f32_16x16x32_bf16 v[28:31], v[150:153], v[174:177], v[28:31]
	v_mfma_f32_16x16x32_bf16 v[24:27], v[158:161], v[174:177], v[24:27]
	v_mfma_f32_16x16x32_bf16 v[12:15], v[150:153], v[166:169], v[12:15]
	v_mfma_f32_16x16x32_bf16 v[8:11], v[158:161], v[166:169], v[8:11]
	s_setprio 0
	s_setprio 1
	v_mfma_f32_16x16x32_bf16 v[52:55], v[130:133], v[186:189], v[52:55]
	v_mfma_f32_16x16x32_bf16 v[48:51], v[138:141], v[186:189], v[48:51]
	v_mfma_f32_16x16x32_bf16 v[36:39], v[130:133], v[178:181], v[36:39]
	v_mfma_f32_16x16x32_bf16 v[32:35], v[138:141], v[178:181], v[32:35]
	v_mfma_f32_16x16x32_bf16 v[20:23], v[130:133], v[170:173], v[20:23]
	v_mfma_f32_16x16x32_bf16 v[16:19], v[138:141], v[170:173], v[16:19]
	v_mfma_f32_16x16x32_bf16 v[4:7], v[130:133], v[162:165], v[4:7]
	v_mfma_f32_16x16x32_bf16 v[0:3], v[138:141], v[162:165], v[0:3]
	v_mfma_f32_16x16x32_bf16 v[52:55], v[134:137], v[190:193], v[52:55]
	v_mfma_f32_16x16x32_bf16 v[48:51], v[142:145], v[190:193], v[48:51]
	v_mfma_f32_16x16x32_bf16 v[36:39], v[134:137], v[182:185], v[36:39]
	v_mfma_f32_16x16x32_bf16 v[32:35], v[142:145], v[182:185], v[32:35]
	v_mfma_f32_16x16x32_bf16 v[20:23], v[134:137], v[174:177], v[20:23]
	v_mfma_f32_16x16x32_bf16 v[16:19], v[142:145], v[174:177], v[16:19]
	v_mfma_f32_16x16x32_bf16 v[4:7], v[134:137], v[166:169], v[4:7]
	v_mfma_f32_16x16x32_bf16 v[0:3], v[142:145], v[166:169], v[0:3]
	s_setprio 0
	s_branch .LBB0_412
